# P1 K-loop: first two super-phase waits after an epilogue relaxed to vmcnt(24) so z stores drain under the first MFMA blocks
# baseline (speedup 1.0000x reference)
; #define PG8_WAIT_V(n) asm volatile("s_waitcnt vmcnt(" #n ")" ::: "memory")
; template <class Epi, class Sched, bool ALIGN_EPI = false, bool SP2 = false>
; __device__ __forceinline__ void gemm_phase(PG8_LAS unsigned char* lds, const Gemm g, const Sched& S, const Epi& E) {
;     const int tid = tid_fresh(), wid = __builtin_amdgcn_readfirstlane(tid >> 6), lane = tid & 63, wr = wid >> 2, wc = wid & 3, fr = lane & 15, fq = lane >> 4;
;     const int K = g.K, nt = K / BK;
;     unsigned voffA[2], voffB[2];
; #pragma unroll
;     for (int i = 0; i < 2; ++i) { int R, C; stage_rc(tid * 16 + i * 8192, R, C); const int Rb = Epi::PERM ? ((R & ~31) + perm32(R & 31)) : R;
;         voffA[i] = (unsigned)(R * g.lda + C) * 2u; voffB[i] = (unsigned)(Rb * g.ldb + C) * 2u; }
;     const size_t kstep = (size_t)(BK * 2);
;     const size_t hstepA = (size_t)HALF * g.lda * 2, hstepB = (size_t)HALF * g.ldb * 2;
;     const size_t tstepA = 2 * hstepA, tstepB = 2 * hstepB;
;     const unsigned ldsw = (unsigned)wid * 1024u;
;     const int aoff = lds_byte(wr * 64 + fr, fq * 8), boff = lds_byte(wc * 32 + fr, fq * 8);
;     ...
;     Unit cur, nxt; int ui = 0;
;     if (!S.next(0, cur)) return;
;     f32x4 acc[2][2][4][2];
; #pragma unroll
;     for (int a = 0; a < 2; ++a)
; #pragma unroll
;         for (int b = 0; b < 2; ++b)
; #pragma unroll
;             for (int m = 0; m < 4; ++m)
; #pragma unroll
;                 for (int n = 0; n < 2; ++n) acc[a][b][m][n] = (f32x4){0.f, 0.f, 0.f, 0.f};
;     bf16x8 At[4][2], B0[2][2], B1[2][2];
;     const char* cA = (const char*)g.A + (size_t)cur.pm * tstepA; const char* cB = (const char*)g.Bt + (size_t)cur.pn * tstepB;
;     S.a_ready(cur);
;     if constexpr (SP2) {
;         PG8_STAGE(PG8_SB(0, 0), cB, voffB); PG8_STAGE(PG8_SB(0, 1), cB + hstepB, voffB); PG8_STAGE(PG8_SA(0, 0), cA, voffA); PG8_STAGE(PG8_SA(0, 1), cA + hstepA, voffA);
;         if (wr == 1) PG8_BAR;
;         PG8_WAIT_V(2); PG8_BAR;
;         PG8_STAGE(PG8_SB(1, 0), cB + kstep, voffB); PG8_STAGE(PG8_SA(1, 0), cA + kstep, voffA); PG8_STAGE(PG8_SB(1, 1), cB + hstepB + kstep, voffB);
;         PG8_WAIT_V(6); PG8_BAR;
;     } else {
;         PG8_STAGE(PG8_SB(0, 0), cB, voffB); PG8_STAGE(PG8_SA(0, 0), cA, voffA); PG8_STAGE(PG8_SB(0, 1), cB + hstepB, voffB); PG8_STAGE(PG8_SA(0, 1), cA + hstepA, voffA);
;         if (wr == 1) PG8_BAR;
;         PG8_WAIT_V(4); PG8_BAR;
.LBB0_120:
	v_bfe_u32 v15, v14, 4, 2
	v_and_b32_e32 v184, 15, v14
	v_lshlrev_b32_e32 v17, 4, v15
	v_lshlrev_b32_e32 v14, 2, v14
	s_and_b32 s4, s4, 3
	s_lshl_b32 s11, s10, 6
	v_lshl_or_b32 v17, v184, 6, v17
	s_lshl_b32 s10, s10, 13
	v_and_b32_e32 v14, 32, v14
	s_add_i32 m0, s54, 0x18000
	v_lshl_add_u64 v[4:5], v[4:5], 0, s[6:7]
	v_bitop3_b32 v18, v17, s10, v14 bitop3:0xde
	s_lshl_b32 s10, s4, 12
	s_waitcnt vmcnt(2)
	s_barrier
	global_load_lds_dwordx4 v[4:5], off
	v_lshl_add_u64 v[2:3], v[2:3], 0, s[6:7]
	s_add_i32 m0, s54, 0x1a000
	s_add_i32 s24, s54, 0x8000
	s_add_i32 s25, s54, 0xa000
	v_bitop3_b32 v185, v17, s10, v14 bitop3:0xde
	global_load_lds_dwordx4 v[2:3], off
	v_lshl_add_u64 v[0:1], v[0:1], 0, s[6:7]
	s_mov_b32 m0, s24
	s_add_u32 s10, s12, 0x40080
	v_writelane_b32 v253, s11, 23
	global_load_lds_dwordx4 v[0:1], off
	v_lshl_add_u64 v[0:1], v[6:7], 0, s[6:7]
	s_mov_b32 m0, s25
	s_addc_u32 s11, s13, 0
	global_load_lds_dwordx4 v[0:1], off
	s_add_i32 m0, s54, 0x1c000
	v_lshl_add_u64 v[0:1], s[10:11], 0, v[150:151]
	global_load_lds_dwordx4 v[0:1], off
	v_lshl_add_u64 v[0:1], s[10:11], 0, v[154:155]
	s_add_i32 m0, s54, 0x1e000
	s_cmpk_lt_u32 s1, 0x100
	global_load_lds_dwordx4 v[0:1], off
	v_lshlrev_b32_e32 v0, 14, v8
	v_and_b32_e32 v0, 0xffff8000, v0
	v_lshl_add_u32 v0, v9, 11, v0
	v_and_b32_e32 v1, 1, v8
	v_lshl_or_b32 v0, v1, 6, v0
	s_cselect_b64 s[10:11], -1, 0
	v_lshl_add_u32 v160, v10, 1, v0
	v_lshlrev_b32_e32 v0, 14, v11
	v_writelane_b32 v253, s10, 25
	s_bitcmp0_b32 s1, 6
	v_and_b32_e32 v0, 0xffff8000, v0
	s_waitcnt vmcnt(6)
	v_writelane_b32 v253, s11, 26
	s_cselect_b64 s[10:11], -1, 0
	v_cmp_eq_u32_e32 vcc, 0, v15
	v_lshl_add_u32 v0, v12, 11, v0
	v_and_b32_e32 v1, 1, v11
	v_lshlrev_b32_e32 v16, 3, v15
	v_writelane_b32 v253, s10, 27
	v_cndmask_b32_e64 v156, 1.0, -1.0, vcc
	v_lshl_or_b32 v0, v1, 6, v0
	s_mov_b32 s26, 0
	v_writelane_b32 v253, s11, 28
	v_lshl_or_b32 v158, s4, 5, v16
	v_cmp_gt_u32_e64 s[38:39], 2, v15
	v_mov_b32_e32 v157, v156
	v_mov_b32_e32 v161, v143
	v_lshl_add_u32 v162, v13, 1, v0
	v_mov_b32_e32 v163, v143
	v_add_u32_e32 v186, 0, v18
	s_barrier
	s_mov_b32 s100, 0
	s_branch .LBB0_123

; #define PG8_BAR __builtin_amdgcn_s_barrier()
; template <class Epi, class Sched, bool ALIGN_EPI = false, bool SP2 = false>
; __device__ __forceinline__ void gemm_phase(PG8_LAS unsigned char* lds, const Gemm g, const Sched& S, const Epi& E) {
;     ...
;         if (!has_next) break;
; #pragma unroll
;         for (int a = 0; a < 2; ++a)
; #pragma unroll
;             for (int b = 0; b < 2; ++b)
; #pragma unroll
;                 for (int m = 0; m < 4; ++m)
; #pragma unroll
;                     for (int n = 0; n < 2; ++n) acc[a][b][m][n] = (f32x4){0.f, 0.f, 0.f, 0.f};
;         cur = nxt; cA = nA; cB = nB; ++ui;
;         if constexpr (ALIGN_EPI) { if (wr == 1) PG8_BAR; }
;     }
.LBB0_122:
	s_andn2_b64 vcc, exec, s[12:13]
	s_mov_b32 s48, s28
	s_mov_b32 s18, s30
	s_mov_b64 s[12:13], s[36:37]
	s_mov_b64 s[42:43], s[20:21]
	s_mov_b32 s100, 1
	s_cbranch_vccz .LBB0_320

; #define PG8_STAGE(bufoff, gbase, voff) do { _Pragma("unroll") for (int _i = 0; _i < 2; ++_i) \
;         __builtin_amdgcn_global_load_lds((const unsigned*)((const char*)(gbase) + (voff)[_i]), (PG8_LAS unsigned*)(lds + (bufoff) + ldsw + _i * 8192), 16, 0, 0); } while (0)
; #define PG8_LDA(dst, b, h) do { _Pragma("unroll") for (int m = 0; m < 4; ++m) _Pragma("unroll") for (int k = 0; k < 2; ++k) dst[m][k] = *(const PG8_LAS bf16x8*)(lds + PG8_SA(b, h) + aoff + m * 2048 + k * 1024); } while (0)
; #define PG8_LDB(dst, b, h) do { _Pragma("unroll") for (int n = 0; n < 2; ++n) _Pragma("unroll") for (int k = 0; k < 2; ++k) dst[n][k] = *(const PG8_LAS bf16x8*)(lds + PG8_SB(b, h) + boff + n * 2048 + k * 1024); } while (0)
; #define PG8_MMA(ai, bj, At, Bt) do { __builtin_amdgcn_s_setprio(1); _Pragma("unroll") for (int m = 0; m < 4; ++m) _Pragma("unroll") for (int n = 0; n < 2; ++n) _Pragma("unroll") for (int k = 0; k < 2; ++k) \
;         acc[ai][bj][m][n] = __builtin_amdgcn_mfma_f32_16x16x32_bf16(Bt[n][k], At[m][k], acc[ai][bj][m][n], 0, 0, 0); __builtin_amdgcn_s_setprio(0); } while (0)
; #define PG8_WAIT_V(n) asm volatile("s_waitcnt vmcnt(" #n ")" ::: "memory")
; #define PG8_WAIT_L(n) asm volatile("s_waitcnt lgkmcnt(" #n ")" ::: "memory")
; #define PG8_BAR __builtin_amdgcn_s_barrier()
; #define PG8_SCHED __builtin_amdgcn_sched_barrier(0)
; template <class Epi, class Sched, bool ALIGN_EPI = false, bool SP2 = false>
; __device__ __forceinline__ void gemm_phase(PG8_LAS unsigned char* lds, const Gemm g, const Sched& S, const Epi& E) {
;     ...
;             PG8_LDB(B0, 0, 0); PG8_LDB(B1, 0, 1); PG8_SCHED; PG8_LDA(At, 0, 0); PG8_STAGE(PG8_SA(1, 1), a1 + hstepA, voffA);
;             PG8_WAIT_V(8); PG8_WAIT_L(0); PG8_BAR; PG8_MMA(0, 0, At, B0); PG8_MMA(0, 1, At, B1); PG8_BAR; PG8_SCHED;
;             PG8_LDA(At, 0, 1); PG8_STAGE(PG8_SB(0, 0), b2, voffB); PG8_STAGE(PG8_SB(0, 1), b2 + hstepB, voffB); PG8_STAGE(PG8_SA(0, 0), a2, voffA);
;             PG8_WAIT_V(8); PG8_WAIT_L(0); PG8_BAR; PG8_MMA(1, 0, At, B0); PG8_MMA(1, 1, At, B1); PG8_BAR; PG8_SCHED;
.LBB0_130:
	s_add_u32 s12, s42, 0xfffc0080
	s_addc_u32 s13, s43, -1
	s_add_i32 s22, 0, 0x10000
	s_cmp_eq_u32 s19, 12
	s_cselect_b32 s45, s1, s13
	s_cselect_b32 s44, s4, s12
	v_add_u32_e32 v8, s22, v185
	s_cselect_b32 s13, s10, s15
	s_cselect_b32 s12, s11, s14
	s_add_i32 s27, 0, 0x14000
	ds_read_b128 v[0:3], v8
	ds_read_b128 v[4:7], v8 offset:1024
	ds_read_b128 v[50:53], v8 offset:2048
	ds_read_b128 v[164:167], v8 offset:3072
	v_add_u32_e32 v8, s27, v185
	ds_read_b128 v[168:171], v8
	ds_read_b128 v[172:175], v8 offset:1024
	ds_read_b128 v[188:191], v8 offset:2048
	ds_read_b128 v[192:195], v8 offset:3072
	v_lshl_add_u64 v[8:9], s[42:43], 0, v[160:161]
	s_add_i32 m0, s54, 0xc000
	ds_read_b128 v[196:199], v186
	ds_read_b128 v[200:203], v186 offset:1024
	ds_read_b128 v[204:207], v186 offset:2048
	ds_read_b128 v[208:211], v186 offset:3072
	ds_read_b128 v[212:215], v186 offset:4096
	ds_read_b128 v[216:219], v186 offset:5120
	ds_read_b128 v[220:223], v186 offset:6144
	ds_read_b128 v[224:227], v186 offset:7168
	global_load_lds_dwordx4 v[8:9], off
	v_lshl_add_u64 v[8:9], s[42:43], 0, v[162:163]
	s_add_i32 m0, s54, 0xe000
	s_nop 0
	global_load_lds_dwordx4 v[8:9], off
	s_cmp_lg_u32 s100, 0
	s_cbranch_scc1 .Lkr1_a
	s_waitcnt vmcnt(8)
.Lkr1_b:
	s_waitcnt lgkmcnt(0)
	s_barrier
	s_setprio 1
	s_waitcnt lgkmcnt(0)
	v_mfma_f32_16x16x32_bf16 v[134:137], v[0:3], v[196:199], v[134:137]
	v_mfma_f32_16x16x32_bf16 v[138:141], v[50:53], v[196:199], v[138:141]
	v_mfma_f32_16x16x32_bf16 v[118:121], v[0:3], v[204:207], v[118:121]
	v_mfma_f32_16x16x32_bf16 v[122:125], v[50:53], v[204:207], v[122:125]
	v_mfma_f32_16x16x32_bf16 v[106:109], v[0:3], v[212:215], v[106:109]
	v_mfma_f32_16x16x32_bf16 v[102:105], v[50:53], v[212:215], v[102:105]
	v_mfma_f32_16x16x32_bf16 v[86:89], v[0:3], v[220:223], v[86:89]
	v_mfma_f32_16x16x32_bf16 v[90:93], v[50:53], v[220:223], v[90:93]
	v_mfma_f32_16x16x32_bf16 v[134:137], v[4:7], v[200:203], v[134:137]
	v_mfma_f32_16x16x32_bf16 v[138:141], v[164:167], v[200:203], v[138:141]
	v_mfma_f32_16x16x32_bf16 v[118:121], v[4:7], v[208:211], v[118:121]
	v_mfma_f32_16x16x32_bf16 v[122:125], v[164:167], v[208:211], v[122:125]
	v_mfma_f32_16x16x32_bf16 v[106:109], v[4:7], v[216:219], v[106:109]
	v_mfma_f32_16x16x32_bf16 v[102:105], v[164:167], v[216:219], v[102:105]
	v_mfma_f32_16x16x32_bf16 v[86:89], v[4:7], v[224:227], v[86:89]
	v_mfma_f32_16x16x32_bf16 v[90:93], v[164:167], v[224:227], v[90:93]
	s_setprio 0
	s_setprio 1
	v_mfma_f32_16x16x32_bf16 v[126:129], v[168:171], v[196:199], v[126:129]
	v_mfma_f32_16x16x32_bf16 v[130:133], v[188:191], v[196:199], v[130:133]
	v_mfma_f32_16x16x32_bf16 v[110:113], v[168:171], v[204:207], v[110:113]
	v_mfma_f32_16x16x32_bf16 v[114:117], v[188:191], v[204:207], v[114:117]
	v_mfma_f32_16x16x32_bf16 v[98:101], v[168:171], v[212:215], v[98:101]
	v_mfma_f32_16x16x32_bf16 v[94:97], v[188:191], v[212:215], v[94:97]
	v_mfma_f32_16x16x32_bf16 v[78:81], v[168:171], v[220:223], v[78:81]
	v_mfma_f32_16x16x32_bf16 v[82:85], v[188:191], v[220:223], v[82:85]
	v_mfma_f32_16x16x32_bf16 v[126:129], v[172:175], v[200:203], v[126:129]
	v_mfma_f32_16x16x32_bf16 v[130:133], v[192:195], v[200:203], v[130:133]
	v_mfma_f32_16x16x32_bf16 v[110:113], v[172:175], v[208:211], v[110:113]
	v_mfma_f32_16x16x32_bf16 v[114:117], v[192:195], v[208:211], v[114:117]
	v_mfma_f32_16x16x32_bf16 v[98:101], v[172:175], v[216:219], v[98:101]
	v_mfma_f32_16x16x32_bf16 v[94:97], v[192:195], v[216:219], v[94:97]
	v_mfma_f32_16x16x32_bf16 v[78:81], v[172:175], v[224:227], v[78:81]
	v_mfma_f32_16x16x32_bf16 v[82:85], v[192:195], v[224:227], v[82:85]
	s_setprio 0
	s_barrier
	s_add_i32 s22, s22, s33
	v_lshl_add_u64 v[176:177], s[12:13], 0, v[150:151]
	s_mov_b32 m0, s22
	ds_read_b128 v[196:199], v186 offset:16384
	ds_read_b128 v[200:203], v186 offset:17408
	ds_read_b128 v[204:207], v186 offset:18432
	ds_read_b128 v[208:211], v186 offset:19456
	ds_read_b128 v[212:215], v186 offset:20480
	ds_read_b128 v[216:219], v186 offset:21504
	ds_read_b128 v[220:223], v186 offset:22528
	ds_read_b128 v[224:227], v186 offset:23552
	global_load_lds_dwordx4 v[176:177], off
	s_add_i32 m0, s22, 0x2000
	s_add_u32 s22, s12, 0x40000
	v_lshl_add_u64 v[178:179], s[12:13], 0, v[154:155]
	s_addc_u32 s23, s13, 0
	s_add_i32 s27, s27, s33
	global_load_lds_dwordx4 v[178:179], off
	v_lshl_add_u64 v[8:9], s[22:23], 0, v[150:151]
	s_mov_b32 m0, s27
	v_lshl_add_u64 v[228:229], s[44:45], 0, v[148:149]
	global_load_lds_dwordx4 v[8:9], off
	v_lshl_add_u64 v[8:9], s[22:23], 0, v[154:155]
	s_add_i32 m0, s27, 0x2000
	v_lshl_add_u64 v[230:231], s[44:45], 0, v[152:153]
	global_load_lds_dwordx4 v[8:9], off
	s_mov_b32 m0, s54
	s_nop 0
	global_load_lds_dwordx4 v[228:229], off
	s_mov_b32 m0, s55
	s_nop 0
	global_load_lds_dwordx4 v[230:231], off
	s_cmp_lg_u32 s100, 0
	s_cbranch_scc1 .Lkr2_a
	s_waitcnt vmcnt(8)
; #define PG8_STAGE(bufoff, gbase, voff) do { _Pragma("unroll") for (int _i = 0; _i < 2; ++_i) \
;         __builtin_amdgcn_global_load_lds((const unsigned*)((const char*)(gbase) + (voff)[_i]), (PG8_LAS unsigned*)(lds + (bufoff) + ldsw + _i * 8192), 16, 0, 0); } while (0)
; #define PG8_LDA(dst, b, h) do { _Pragma("unroll") for (int m = 0; m < 4; ++m) _Pragma("unroll") for (int k = 0; k < 2; ++k) dst[m][k] = *(const PG8_LAS bf16x8*)(lds + PG8_SA(b, h) + aoff + m * 2048 + k * 1024); } while (0)
; #define PG8_LDB(dst, b, h) do { _Pragma("unroll") for (int n = 0; n < 2; ++n) _Pragma("unroll") for (int k = 0; k < 2; ++k) dst[n][k] = *(const PG8_LAS bf16x8*)(lds + PG8_SB(b, h) + boff + n * 2048 + k * 1024); } while (0)
; #define PG8_MMA(ai, bj, At, Bt) do { __builtin_amdgcn_s_setprio(1); _Pragma("unroll") for (int m = 0; m < 4; ++m) _Pragma("unroll") for (int n = 0; n < 2; ++n) _Pragma("unroll") for (int k = 0; k < 2; ++k) \
;         acc[ai][bj][m][n] = __builtin_amdgcn_mfma_f32_16x16x32_bf16(Bt[n][k], At[m][k], acc[ai][bj][m][n], 0, 0, 0); __builtin_amdgcn_s_setprio(0); } while (0)
; #define PG8_WAIT_V(n) asm volatile("s_waitcnt vmcnt(" #n ")" ::: "memory")
; #define PG8_WAIT_L(n) asm volatile("s_waitcnt lgkmcnt(" #n ")" ::: "memory")
; #define PG8_BAR __builtin_amdgcn_s_barrier()
; #define PG8_SCHED __builtin_amdgcn_sched_barrier(0)
; template <class Epi, class Sched, bool ALIGN_EPI = false, bool SP2 = false>
; __device__ __forceinline__ void gemm_phase(PG8_LAS unsigned char* lds, const Gemm g, const Sched& S, const Epi& E) {
;     ...
;             PG8_LDA(At, 0, 1); PG8_STAGE(PG8_SB(0, 0), b2, voffB); PG8_STAGE(PG8_SB(0, 1), b2 + hstepB, voffB); PG8_STAGE(PG8_SA(0, 0), a2, voffA);
;             PG8_WAIT_V(8); PG8_WAIT_L(0); PG8_BAR; PG8_MMA(1, 0, At, B0); PG8_MMA(1, 1, At, B1); PG8_BAR; PG8_SCHED;
;             PG8_LDB(B0, 1, 0); PG8_LDB(B1, 1, 1); PG8_SCHED; PG8_LDA(At, 1, 0); PG8_STAGE(PG8_SA(0, 1), a2 + hstepA, voffA);
;             PG8_WAIT_V(8); PG8_WAIT_L(0); PG8_BAR; PG8_MMA(0, 0, At, B0); PG8_MMA(0, 1, At, B1); PG8_BAR; PG8_SCHED;
.Lkr2_b:
	s_mov_b32 s100, 0
	s_waitcnt lgkmcnt(0)
	s_barrier
	s_setprio 1
	s_waitcnt lgkmcnt(0)
	v_mfma_f32_16x16x32_bf16 v[70:73], v[0:3], v[196:199], v[70:73]
	v_mfma_f32_16x16x32_bf16 v[74:77], v[50:53], v[196:199], v[74:77]
	v_mfma_f32_16x16x32_bf16 v[54:57], v[0:3], v[204:207], v[54:57]
	v_mfma_f32_16x16x32_bf16 v[58:61], v[50:53], v[204:207], v[58:61]
	v_mfma_f32_16x16x32_bf16 v[38:41], v[0:3], v[212:215], v[38:41]
	v_mfma_f32_16x16x32_bf16 v[34:37], v[50:53], v[212:215], v[34:37]
	v_mfma_f32_16x16x32_bf16 v[0:3], v[0:3], v[220:223], v[18:21]
	v_mfma_f32_16x16x32_bf16 v[70:73], v[4:7], v[200:203], v[70:73]
	v_mfma_f32_16x16x32_bf16 v[74:77], v[164:167], v[200:203], v[74:77]
	v_mfma_f32_16x16x32_bf16 v[54:57], v[4:7], v[208:211], v[54:57]
	v_mfma_f32_16x16x32_bf16 v[58:61], v[164:167], v[208:211], v[58:61]
	v_mfma_f32_16x16x32_bf16 v[38:41], v[4:7], v[216:219], v[38:41]
	v_mfma_f32_16x16x32_bf16 v[34:37], v[164:167], v[216:219], v[34:37]
	v_mfma_f32_16x16x32_bf16 v[0:3], v[4:7], v[224:227], v[0:3]
	v_mfma_f32_16x16x32_bf16 v[4:7], v[50:53], v[220:223], v[22:25]
	v_mfma_f32_16x16x32_bf16 v[4:7], v[164:167], v[224:227], v[4:7]
	s_setprio 0
	s_setprio 1
	v_mfma_f32_16x16x32_bf16 v[18:21], v[168:171], v[196:199], v[62:65]
	v_mfma_f32_16x16x32_bf16 v[50:53], v[172:175], v[200:203], v[18:21]
	v_mfma_f32_16x16x32_bf16 v[18:21], v[188:191], v[196:199], v[66:69]
	v_mfma_f32_16x16x32_bf16 v[66:69], v[192:195], v[200:203], v[18:21]
	v_mfma_f32_16x16x32_bf16 v[18:21], v[168:171], v[204:207], v[42:45]
	v_mfma_f32_16x16x32_bf16 v[42:45], v[172:175], v[208:211], v[18:21]
	v_mfma_f32_16x16x32_bf16 v[18:21], v[188:191], v[204:207], v[46:49]
	v_mfma_f32_16x16x32_bf16 v[46:49], v[192:195], v[208:211], v[18:21]
	v_mfma_f32_16x16x32_bf16 v[18:21], v[168:171], v[212:215], v[30:33]
	v_mfma_f32_16x16x32_bf16 v[30:33], v[172:175], v[216:219], v[18:21]
	v_mfma_f32_16x16x32_bf16 v[18:21], v[188:191], v[212:215], v[26:29]
	v_mfma_f32_16x16x32_bf16 v[14:17], v[168:171], v[220:223], v[14:17]
	v_mfma_f32_16x16x32_bf16 v[8:11], v[188:191], v[220:223], v[10:13]
	v_mfma_f32_16x16x32_bf16 v[26:29], v[192:195], v[216:219], v[18:21]
	v_mfma_f32_16x16x32_bf16 v[14:17], v[172:175], v[224:227], v[14:17]
	v_mfma_f32_16x16x32_bf16 v[8:11], v[192:195], v[224:227], v[8:11]
	s_setprio 0
	s_barrier
	s_add_i32 s27, 0, 0x18000
	v_add_u32_e32 v12, s27, v185
	s_add_i32 s29, 0, 0x1c000
	ds_read_b128 v[18:21], v12
	ds_read_b128 v[22:25], v12 offset:1024
	ds_read_b128 v[62:65], v12 offset:2048
	ds_read_b128 v[164:167], v12 offset:3072
	v_add_u32_e32 v12, s29, v185
	ds_read_b128 v[168:171], v12
	ds_read_b128 v[172:175], v12 offset:1024
	ds_read_b128 v[188:191], v12 offset:2048
	ds_read_b128 v[192:195], v12 offset:3072
	s_add_u32 s22, s44, 0x40000
	s_addc_u32 s23, s45, 0
	s_mov_b32 m0, s16
	v_lshl_add_u64 v[12:13], s[22:23], 0, v[148:149]
	ds_read_b128 v[196:199], v186 offset:32768
	ds_read_b128 v[200:203], v186 offset:33792
	ds_read_b128 v[204:207], v186 offset:34816
	ds_read_b128 v[208:211], v186 offset:35840
	ds_read_b128 v[212:215], v186 offset:36864
	ds_read_b128 v[216:219], v186 offset:37888
	ds_read_b128 v[220:223], v186 offset:38912
	ds_read_b128 v[224:227], v186 offset:39936
	global_load_lds_dwordx4 v[12:13], off
	v_lshl_add_u64 v[12:13], s[22:23], 0, v[152:153]
	s_mov_b32 m0, s17
	s_nop 0
	global_load_lds_dwordx4 v[12:13], off
	s_waitcnt vmcnt(8)
	s_waitcnt lgkmcnt(0)
	s_barrier
	s_setprio 1
	s_waitcnt lgkmcnt(0)
	v_mfma_f32_16x16x32_bf16 v[134:137], v[18:21], v[196:199], v[134:137]
	v_mfma_f32_16x16x32_bf16 v[138:141], v[62:65], v[196:199], v[138:141]
	v_mfma_f32_16x16x32_bf16 v[118:121], v[18:21], v[204:207], v[118:121]
	v_mfma_f32_16x16x32_bf16 v[122:125], v[62:65], v[204:207], v[122:125]
	v_mfma_f32_16x16x32_bf16 v[106:109], v[18:21], v[212:215], v[106:109]
	v_mfma_f32_16x16x32_bf16 v[102:105], v[62:65], v[212:215], v[102:105]
	v_mfma_f32_16x16x32_bf16 v[86:89], v[18:21], v[220:223], v[86:89]
	v_mfma_f32_16x16x32_bf16 v[90:93], v[62:65], v[220:223], v[90:93]
	v_mfma_f32_16x16x32_bf16 v[134:137], v[22:25], v[200:203], v[134:137]
	v_mfma_f32_16x16x32_bf16 v[138:141], v[164:167], v[200:203], v[138:141]
	v_mfma_f32_16x16x32_bf16 v[118:121], v[22:25], v[208:211], v[118:121]
	v_mfma_f32_16x16x32_bf16 v[122:125], v[164:167], v[208:211], v[122:125]
	v_mfma_f32_16x16x32_bf16 v[106:109], v[22:25], v[216:219], v[106:109]
	v_mfma_f32_16x16x32_bf16 v[102:105], v[164:167], v[216:219], v[102:105]
	v_mfma_f32_16x16x32_bf16 v[86:89], v[22:25], v[224:227], v[86:89]
	v_mfma_f32_16x16x32_bf16 v[90:93], v[164:167], v[224:227], v[90:93]
	s_setprio 0
	s_setprio 1
	v_mfma_f32_16x16x32_bf16 v[126:129], v[168:171], v[196:199], v[126:129]
	v_mfma_f32_16x16x32_bf16 v[130:133], v[188:191], v[196:199], v[130:133]
	v_mfma_f32_16x16x32_bf16 v[110:113], v[168:171], v[204:207], v[110:113]
	v_mfma_f32_16x16x32_bf16 v[114:117], v[188:191], v[204:207], v[114:117]
	v_mfma_f32_16x16x32_bf16 v[98:101], v[168:171], v[212:215], v[98:101]
	v_mfma_f32_16x16x32_bf16 v[94:97], v[188:191], v[212:215], v[94:97]
	v_mfma_f32_16x16x32_bf16 v[78:81], v[168:171], v[220:223], v[78:81]
	v_mfma_f32_16x16x32_bf16 v[82:85], v[188:191], v[220:223], v[82:85]
	v_mfma_f32_16x16x32_bf16 v[126:129], v[172:175], v[200:203], v[126:129]
	v_mfma_f32_16x16x32_bf16 v[130:133], v[192:195], v[200:203], v[130:133]
	v_mfma_f32_16x16x32_bf16 v[110:113], v[172:175], v[208:211], v[110:113]
	v_mfma_f32_16x16x32_bf16 v[114:117], v[192:195], v[208:211], v[114:117]
	v_mfma_f32_16x16x32_bf16 v[98:101], v[172:175], v[216:219], v[98:101]
	v_mfma_f32_16x16x32_bf16 v[94:97], v[192:195], v[216:219], v[94:97]
	v_mfma_f32_16x16x32_bf16 v[78:81], v[172:175], v[224:227], v[78:81]
	v_mfma_f32_16x16x32_bf16 v[82:85], v[192:195], v[224:227], v[82:85]
	s_setprio 0
	s_barrier
; #define PG8_STAGE(bufoff, gbase, voff) do { _Pragma("unroll") for (int _i = 0; _i < 2; ++_i) \
;         __builtin_amdgcn_global_load_lds((const unsigned*)((const char*)(gbase) + (voff)[_i]), (PG8_LAS unsigned*)(lds + (bufoff) + ldsw + _i * 8192), 16, 0, 0); } while (0)
; #define PG8_LDA(dst, b, h) do { _Pragma("unroll") for (int m = 0; m < 4; ++m) _Pragma("unroll") for (int k = 0; k < 2; ++k) dst[m][k] = *(const PG8_LAS bf16x8*)(lds + PG8_SA(b, h) + aoff + m * 2048 + k * 1024); } while (0)
; #define PG8_LDB(dst, b, h) do { _Pragma("unroll") for (int n = 0; n < 2; ++n) _Pragma("unroll") for (int k = 0; k < 2; ++k) dst[n][k] = *(const PG8_LAS bf16x8*)(lds + PG8_SB(b, h) + boff + n * 2048 + k * 1024); } while (0)
; #define PG8_MMA(ai, bj, At, Bt) do { __builtin_amdgcn_s_setprio(1); _Pragma("unroll") for (int m = 0; m < 4; ++m) _Pragma("unroll") for (int n = 0; n < 2; ++n) _Pragma("unroll") for (int k = 0; k < 2; ++k) \
;         acc[ai][bj][m][n] = __builtin_amdgcn_mfma_f32_16x16x32_bf16(Bt[n][k], At[m][k], acc[ai][bj][m][n], 0, 0, 0); __builtin_amdgcn_s_setprio(0); } while (0)
; #define PG8_WAIT_V(n) asm volatile("s_waitcnt vmcnt(" #n ")" ::: "memory")
; #define PG8_WAIT_L(n) asm volatile("s_waitcnt lgkmcnt(" #n ")" ::: "memory")
; #define PG8_BAR __builtin_amdgcn_s_barrier()
; #define PG8_SCHED __builtin_amdgcn_sched_barrier(0)
; template <class Epi, class Sched, bool ALIGN_EPI = false, bool SP2 = false>
; __device__ __forceinline__ void gemm_phase(PG8_LAS unsigned char* lds, const Gemm g, const Sched& S, const Epi& E) {
;     ...
;             PG8_LDB(B0, 1, 0); PG8_LDB(B1, 1, 1); PG8_SCHED; PG8_LDA(At, 1, 0); PG8_STAGE(PG8_SA(0, 1), a2 + hstepA, voffA);
;             PG8_WAIT_V(8); PG8_WAIT_L(0); PG8_BAR; PG8_MMA(0, 0, At, B0); PG8_MMA(0, 1, At, B1); PG8_BAR; PG8_SCHED;
;             PG8_LDA(At, 1, 1); PG8_STAGE(PG8_SB(1, 0), b3, voffB); PG8_STAGE(PG8_SB(1, 1), b3 + hstepB, voffB); PG8_STAGE(PG8_SA(1, 0), a3, voffA);
;             PG8_WAIT_V(8); PG8_WAIT_L(0); PG8_BAR; PG8_MMA(1, 0, At, B0); PG8_MMA(1, 1, At, B1); PG8_BAR; PG8_SCHED;
	s_add_i32 s22, s27, s33
	v_lshl_add_u64 v[12:13], v[176:177], 0, s[6:7]
	s_mov_b32 m0, s22
	ds_read_b128 v[196:199], v186 offset:49152
	ds_read_b128 v[200:203], v186 offset:50176
	ds_read_b128 v[204:207], v186 offset:51200
	ds_read_b128 v[208:211], v186 offset:52224
	ds_read_b128 v[212:215], v186 offset:53248
	ds_read_b128 v[216:219], v186 offset:54272
	ds_read_b128 v[220:223], v186 offset:55296
	ds_read_b128 v[224:227], v186 offset:56320
	global_load_lds_dwordx4 v[12:13], off
	s_add_i32 m0, s22, 0x2000
	s_add_u32 s12, s12, 0x40080
	v_lshl_add_u64 v[12:13], v[178:179], 0, s[6:7]
	s_addc_u32 s13, s13, 0
	s_add_i32 s22, s29, s33
	global_load_lds_dwordx4 v[12:13], off
	v_lshl_add_u64 v[12:13], s[12:13], 0, v[150:151]
	s_mov_b32 m0, s22
	s_nop 0
	global_load_lds_dwordx4 v[12:13], off
	v_lshl_add_u64 v[12:13], s[12:13], 0, v[154:155]
	s_add_i32 m0, s22, 0x2000
	s_nop 0
	global_load_lds_dwordx4 v[12:13], off
	v_lshl_add_u64 v[12:13], v[228:229], 0, s[6:7]
	s_mov_b32 m0, s24
	s_nop 0
	global_load_lds_dwordx4 v[12:13], off
	v_lshl_add_u64 v[12:13], v[230:231], 0, s[6:7]
	s_mov_b32 m0, s25
	s_nop 0
	global_load_lds_dwordx4 v[12:13], off
	s_waitcnt vmcnt(8)
	s_waitcnt lgkmcnt(0)
	s_barrier
	s_setprio 1
	s_waitcnt lgkmcnt(0)
	v_mfma_f32_16x16x32_bf16 v[0:3], v[18:21], v[220:223], v[0:3]
	v_mfma_f32_16x16x32_bf16 v[70:73], v[18:21], v[196:199], v[70:73]
	v_mfma_f32_16x16x32_bf16 v[74:77], v[62:65], v[196:199], v[74:77]
	v_mfma_f32_16x16x32_bf16 v[54:57], v[18:21], v[204:207], v[54:57]
	v_mfma_f32_16x16x32_bf16 v[58:61], v[62:65], v[204:207], v[58:61]
	v_mfma_f32_16x16x32_bf16 v[38:41], v[18:21], v[212:215], v[38:41]
	v_mfma_f32_16x16x32_bf16 v[34:37], v[62:65], v[212:215], v[34:37]
	v_mfma_f32_16x16x32_bf16 v[18:21], v[22:25], v[224:227], v[0:3]
	v_mfma_f32_16x16x32_bf16 v[0:3], v[62:65], v[220:223], v[4:7]
	v_mfma_f32_16x16x32_bf16 v[70:73], v[22:25], v[200:203], v[70:73]
	v_mfma_f32_16x16x32_bf16 v[74:77], v[164:167], v[200:203], v[74:77]
	v_mfma_f32_16x16x32_bf16 v[54:57], v[22:25], v[208:211], v[54:57]
	v_mfma_f32_16x16x32_bf16 v[58:61], v[164:167], v[208:211], v[58:61]
	v_mfma_f32_16x16x32_bf16 v[38:41], v[22:25], v[216:219], v[38:41]
	v_mfma_f32_16x16x32_bf16 v[34:37], v[164:167], v[216:219], v[34:37]
	v_mfma_f32_16x16x32_bf16 v[22:25], v[164:167], v[224:227], v[0:3]
	s_setprio 0
	s_setprio 1
	v_mfma_f32_16x16x32_bf16 v[0:3], v[168:171], v[196:199], v[50:53]
	v_mfma_f32_16x16x32_bf16 v[62:65], v[172:175], v[200:203], v[0:3]
	v_mfma_f32_16x16x32_bf16 v[0:3], v[188:191], v[196:199], v[66:69]
	v_mfma_f32_16x16x32_bf16 v[66:69], v[192:195], v[200:203], v[0:3]
	v_mfma_f32_16x16x32_bf16 v[0:3], v[168:171], v[204:207], v[42:45]
	v_mfma_f32_16x16x32_bf16 v[42:45], v[172:175], v[208:211], v[0:3]
	v_mfma_f32_16x16x32_bf16 v[0:3], v[188:191], v[204:207], v[46:49]
	v_mfma_f32_16x16x32_bf16 v[46:49], v[192:195], v[208:211], v[0:3]
	v_mfma_f32_16x16x32_bf16 v[0:3], v[168:171], v[212:215], v[30:33]
	v_mfma_f32_16x16x32_bf16 v[30:33], v[172:175], v[216:219], v[0:3]
	v_mfma_f32_16x16x32_bf16 v[0:3], v[188:191], v[212:215], v[26:29]
	v_mfma_f32_16x16x32_bf16 v[26:29], v[192:195], v[216:219], v[0:3]
	v_mfma_f32_16x16x32_bf16 v[0:3], v[168:171], v[220:223], v[14:17]
	v_mfma_f32_16x16x32_bf16 v[14:17], v[172:175], v[224:227], v[0:3]
	v_mfma_f32_16x16x32_bf16 v[0:3], v[188:191], v[220:223], v[8:11]
	v_mfma_f32_16x16x32_bf16 v[10:13], v[192:195], v[224:227], v[0:3]
	s_setprio 0
	s_barrier
	s_add_i32 s19, s19, 2
	s_add_u32 s42, s42, 0x100
	s_addc_u32 s43, s43, 0
	s_add_u32 s14, s14, 0x100
	s_addc_u32 s15, s15, 0
	s_cmp_gt_u32 s19, 13
	s_cbranch_scc0 .LBB0_130
	v_readlane_b32 s10, v253, 25
	v_readlane_b32 s11, v253, 26
	s_and_b64 vcc, exec, s[10:11]
	s_cbranch_vccz .LBB0_133
	s_barrier

; #define PG8_STAGE(bufoff, gbase, voff) do { _Pragma("unroll") for (int _i = 0; _i < 2; ++_i) \
;         __builtin_amdgcn_global_load_lds((const unsigned*)((const char*)(gbase) + (voff)[_i]), (PG8_LAS unsigned*)(lds + (bufoff) + ldsw + _i * 8192), 16, 0, 0); } while (0)
; #define PG8_LDA(dst, b, h) do { _Pragma("unroll") for (int m = 0; m < 4; ++m) _Pragma("unroll") for (int k = 0; k < 2; ++k) dst[m][k] = *(const PG8_LAS bf16x8*)(lds + PG8_SA(b, h) + aoff + m * 2048 + k * 1024); } while (0)
; #define PG8_MMA(ai, bj, At, Bt) do { __builtin_amdgcn_s_setprio(1); _Pragma("unroll") for (int m = 0; m < 4; ++m) _Pragma("unroll") for (int n = 0; n < 2; ++n) _Pragma("unroll") for (int k = 0; k < 2; ++k) \
;         acc[ai][bj][m][n] = __builtin_amdgcn_mfma_f32_16x16x32_bf16(Bt[n][k], At[m][k], acc[ai][bj][m][n], 0, 0, 0); __builtin_amdgcn_s_setprio(0); } while (0)
; #define PG8_WAIT_V(n) asm volatile("s_waitcnt vmcnt(" #n ")" ::: "memory")
; #define PG8_WAIT_L(n) asm volatile("s_waitcnt lgkmcnt(" #n ")" ::: "memory")
; #define PG8_BAR __builtin_amdgcn_s_barrier()
; #define PG8_SCHED __builtin_amdgcn_sched_barrier(0)
; template <class Epi, class Sched, bool ALIGN_EPI = false, bool SP2 = false>
; __device__ __forceinline__ void gemm_phase(PG8_LAS unsigned char* lds, const Gemm g, const Sched& S, const Epi& E) {
;     ...
;             PG8_LDA(At, 0, 1); PG8_STAGE(PG8_SB(0, 0), b2, voffB); PG8_STAGE(PG8_SB(0, 1), b2 + hstepB, voffB); PG8_STAGE(PG8_SA(0, 0), a2, voffA);
;             PG8_WAIT_V(8); PG8_WAIT_L(0); PG8_BAR; PG8_MMA(1, 0, At, B0); PG8_MMA(1, 1, At, B1); PG8_BAR; PG8_SCHED;
.Lkr2_a:
	s_waitcnt vmcnt(24)
	s_branch .Lkr2_b
